# nt (streaming) hint on the PREP phase input loads
# baseline (speedup 1.0000x reference)
.LBB0_435:
	v_ashrrev_i32_e32 v15, 4, v14
	v_add_u32_e32 v8, s2, v15
	v_ashrrev_i32_e32 v9, 31, v8
	v_and_b32_e32 v0, 60, v7
	v_lshlrev_b64 v[2:3], 14, v[8:9]
	v_lshl_add_u64 v[2:3], s[8:9], 0, v[2:3]
	v_lshlrev_b32_e32 v0, 2, v0
	v_lshl_add_u64 v[2:3], v[2:3], 0, v[0:1]
	global_load_dwordx4 v[2:5], v[2:3], off nt
	s_andn2_b64 vcc, exec, s[84:85]
	s_cbranch_vccz .LBB0_433
	v_mov_b32_e32 v8, 1.0
	s_branch .LBB0_434

.LBB0_444:
	v_ashrrev_i32_e32 v15, 4, v14
	v_add_u32_e32 v8, s2, v15
	v_ashrrev_i32_e32 v9, 31, v8
	v_and_b32_e32 v0, 60, v7
	v_lshlrev_b64 v[2:3], 14, v[8:9]
	v_lshl_add_u64 v[2:3], s[10:11], 0, v[2:3]
	v_lshlrev_b32_e32 v0, 2, v0
	v_lshl_add_u64 v[2:3], v[2:3], 0, v[0:1]
	global_load_dwordx4 v[2:5], v[2:3], off nt
	s_andn2_b64 vcc, exec, s[84:85]
	s_cbranch_vccz .LBB0_442
	v_mov_b32_e32 v8, 1.0
	s_branch .LBB0_443

.LBB0_469:
	v_ashrrev_i32_e32 v9, 4, v8
	v_add_u32_e32 v10, s2, v9
	v_ashrrev_i32_e32 v11, 31, v10
	v_lshlrev_b64 v[10:11], 12, v[10:11]
	v_lshlrev_b32_e32 v0, 2, v3
	v_lshl_add_u64 v[10:11], s[10:11], 0, v[10:11]
	v_and_b32_e32 v0, 0xf0, v0
	v_lshl_add_u64 v[10:11], v[10:11], 0, v[0:1]
	global_load_dwordx4 v[10:13], v[10:11], off nt
	v_mul_lo_u32 v9, v9, s27
	v_add3_u32 v0, 0, v9, v0
	v_cmp_lt_i32_e64 s[0:1], s33, v8
	v_add_u32_e32 v3, 0x800, v3
	s_or_b64 s[12:13], s[0:1], s[12:13]
	s_waitcnt vmcnt(0)
	ds_write2_b32 v0, v10, v11 offset1:1
	ds_write2_b32 v0, v12, v13 offset0:2 offset1:3
	v_add_u32_e32 v0, 0x200, v8
	v_mov_b32_e32 v8, v0
	s_andn2_b64 exec, exec, s[12:13]
	s_cbranch_execnz .LBB0_469
	s_branch .LBB0_466

.LBB0_487:
	v_ashrrev_i32_e32 v9, 4, v8
	v_add_u32_e32 v10, s2, v9
	v_ashrrev_i32_e32 v11, 31, v10
	v_lshlrev_b64 v[10:11], 12, v[10:11]
	v_lshlrev_b32_e32 v0, 2, v3
	v_lshl_add_u64 v[10:11], s[8:9], 0, v[10:11]
	v_and_b32_e32 v0, 0xf0, v0
	v_lshl_add_u64 v[10:11], v[10:11], 0, v[0:1]
	global_load_dwordx4 v[10:13], v[10:11], off nt
	v_mul_lo_u32 v9, v9, s27
	v_add3_u32 v0, 0, v9, v0
	v_cmp_lt_i32_e64 s[0:1], s33, v8
	v_add_u32_e32 v3, 0x800, v3
	s_or_b64 s[10:11], s[0:1], s[10:11]
	s_waitcnt vmcnt(0)
	ds_write2_b32 v0, v10, v11 offset1:1
	ds_write2_b32 v0, v12, v13 offset0:2 offset1:3
	v_add_u32_e32 v0, 0x200, v8
	v_mov_b32_e32 v8, v0
	s_andn2_b64 exec, exec, s[10:11]
	s_cbranch_execnz .LBB0_487
	s_branch .LBB0_484

.LBB0_495:
	v_ashrrev_i32_e32 v15, 4, v14
	v_and_b32_e32 v0, 60, v7
	v_add_u32_e32 v8, s2, v15
	v_mov_b64_e32 v[2:3], s[10:11]
	v_mad_i64_i32 v[2:3], s[16:17], v8, s18, v[2:3]
	v_lshlrev_b32_e32 v0, 2, v0
	v_lshl_add_u64 v[2:3], v[2:3], 0, v[0:1]
	global_load_dwordx4 v[2:5], v[2:3], off nt
	s_andn2_b64 vcc, exec, s[88:89]
	s_cbranch_vccz .LBB0_493
	v_mov_b32_e32 v8, 1.0
	s_branch .LBB0_494

.LBB0_504:
	v_ashrrev_i32_e32 v15, 4, v14
	v_and_b32_e32 v0, 60, v7
	v_add_u32_e32 v8, s2, v15
	v_mov_b64_e32 v[2:3], s[8:9]
	v_mad_i64_i32 v[2:3], s[14:15], v8, s18, v[2:3]
	v_lshlrev_b32_e32 v0, 2, v0
	v_lshl_add_u64 v[2:3], v[2:3], 0, v[0:1]
	global_load_dwordx4 v[2:5], v[2:3], off nt
	s_andn2_b64 vcc, exec, s[88:89]
	s_cbranch_vccz .LBB0_502
	v_mov_b32_e32 v8, 1.0
	s_branch .LBB0_503

.LBB0_523:
	v_ashrrev_i32_e32 v9, 4, v8
	v_add_u32_e32 v10, s2, v9
	v_ashrrev_i32_e32 v11, 31, v10
	v_lshlrev_b64 v[12:13], 14, v[10:11]
	v_lshlrev_b32_e32 v0, 2, v3
	v_lshl_add_u64 v[12:13], s[10:11], 0, v[12:13]
	v_and_b32_e32 v0, 0xf0, v0
	v_lshl_add_u64 v[12:13], v[12:13], 0, v[0:1]
	v_lshl_add_u64 v[10:11], v[10:11], 2, s[16:17]
	global_load_dword v14, v[10:11], off
	v_mul_lo_u32 v9, v9, s27
	global_load_dwordx4 v[10:13], v[12:13], off nt
	v_add3_u32 v0, 0, v9, v0
	v_cmp_lt_i32_e64 s[0:1], s33, v8
	v_add_u32_e32 v3, 0x800, v3
	s_or_b64 s[12:13], s[0:1], s[12:13]
	s_waitcnt vmcnt(0)
	v_pk_mul_f32 v[10:11], v[10:11], v[14:15] op_sel_hi:[1,0]
	ds_write2_b32 v0, v10, v11 offset1:1
	v_pk_mul_f32 v[10:11], v[12:13], v[14:15] op_sel_hi:[1,0]
	ds_write2_b32 v0, v10, v11 offset0:2 offset1:3
	v_add_u32_e32 v0, 0x200, v8
	v_mov_b32_e32 v8, v0
	s_andn2_b64 exec, exec, s[12:13]
	s_cbranch_execnz .LBB0_523
	s_branch .LBB0_520

.LBB0_535:
	v_ashrrev_i32_e32 v9, 4, v8
	v_add_u32_e32 v10, s2, v9
	v_mov_b64_e32 v[12:13], s[10:11]
	s_movk_i32 s0, 0x4800
	v_lshlrev_b32_e32 v0, 2, v3
	v_ashrrev_i32_e32 v11, 31, v10
	v_mad_i64_i32 v[12:13], s[0:1], v10, s0, v[12:13]
	v_and_b32_e32 v0, 0xf0, v0
	v_lshl_add_u64 v[12:13], v[12:13], 0, v[0:1]
	v_lshl_add_u64 v[10:11], v[10:11], 2, s[16:17]
	global_load_dword v14, v[10:11], off
	v_mul_lo_u32 v9, v9, s27
	global_load_dwordx4 v[10:13], v[12:13], off nt
	v_add3_u32 v0, 0, v9, v0
	v_cmp_lt_i32_e64 s[0:1], s33, v8
	v_add_u32_e32 v3, 0x800, v3
	s_or_b64 s[12:13], s[0:1], s[12:13]
	s_waitcnt vmcnt(0)
	v_pk_mul_f32 v[10:11], v[10:11], v[14:15] op_sel_hi:[1,0]
	ds_write2_b32 v0, v10, v11 offset1:1
	v_pk_mul_f32 v[10:11], v[12:13], v[14:15] op_sel_hi:[1,0]
	ds_write2_b32 v0, v10, v11 offset0:2 offset1:3
	v_add_u32_e32 v0, 0x200, v8
	v_mov_b32_e32 v8, v0
	s_andn2_b64 exec, exec, s[12:13]
	s_cbranch_execnz .LBB0_535
	s_branch .LBB0_532

.LBB0_548:
	v_cmp_lt_i32_e64 s[0:1], s87, v2
	v_mov_b64_e32 v[10:11], v[2:3]
	s_waitcnt lgkmcnt(0)
	v_mov_b64_e32 v[12:13], v[8:9]
	s_and_saveexec_b64 s[8:9], s[0:1]
	v_add_u32_e32 v10, 0xffff8000, v2
	v_mov_b32_e32 v11, v1
	v_lshlrev_b64 v[10:11], 12, v[10:11]
	v_lshl_add_u64 v[12:13], s[38:39], 0, v[10:11]
	v_mov_b32_e32 v10, v2
	v_mov_b32_e32 v11, v1
	s_or_b64 exec, exec, s[8:9]
	v_lshl_add_u64 v[14:15], v[12:13], 0, v[0:1]
	global_load_dwordx4 v[22:25], v[14:15], off nt
	v_lshlrev_b64 v[12:13], 11, v[10:11]
	v_lshl_add_u64 v[12:13], v[4:5], 0, v[12:13]
	s_waitcnt vmcnt(0)
	v_mul_f32_e32 v26, v23, v23
	v_fmac_f32_e32 v26, v22, v22
	v_and_b32_sdwa v27, v24, v152 dst_sel:DWORD dst_unused:UNUSED_PAD src0_sel:WORD_1 src1_sel:DWORD
	v_and_b32_sdwa v28, v22, v152 dst_sel:DWORD dst_unused:UNUSED_PAD src0_sel:WORD_1 src1_sel:DWORD
	v_fmac_f32_e32 v26, v24, v24
	v_add3_u32 v22, v22, v28, s87
	v_add3_u32 v24, v24, v27, s87
	v_and_b32_sdwa v27, v25, v152 dst_sel:DWORD dst_unused:UNUSED_PAD src0_sel:WORD_1 src1_sel:DWORD
	v_and_b32_sdwa v28, v23, v152 dst_sel:DWORD dst_unused:UNUSED_PAD src0_sel:WORD_1 src1_sel:DWORD
	v_fmac_f32_e32 v26, v25, v25
	v_add3_u32 v25, v25, v27, s87
	v_add3_u32 v23, v23, v28, s87
	v_and_b32_e32 v25, 0xffff0000, v25
	v_and_b32_e32 v27, 0xffff0000, v23
	v_or_b32_sdwa v23, v25, v24 dst_sel:DWORD dst_unused:UNUSED_PAD src0_sel:DWORD src1_sel:WORD_1
	v_or_b32_sdwa v22, v27, v22 dst_sel:DWORD dst_unused:UNUSED_PAD src0_sel:DWORD src1_sel:WORD_1
	global_store_dwordx2 v[12:13], v[22:23], off
	global_load_dwordx4 v[22:25], v[14:15], off offset:1024 nt
	s_waitcnt vmcnt(0)
	v_mul_f32_e32 v27, v23, v23
	v_fmac_f32_e32 v27, v22, v22
	v_fmac_f32_e32 v27, v24, v24
	v_fmac_f32_e32 v27, v25, v25
	v_add_f32_e32 v26, v26, v27
	v_and_b32_sdwa v27, v24, v152 dst_sel:DWORD dst_unused:UNUSED_PAD src0_sel:WORD_1 src1_sel:DWORD
	v_and_b32_sdwa v28, v22, v152 dst_sel:DWORD dst_unused:UNUSED_PAD src0_sel:WORD_1 src1_sel:DWORD
	v_add3_u32 v22, v22, v28, s87
	v_add3_u32 v24, v24, v27, s87
	v_and_b32_sdwa v27, v25, v152 dst_sel:DWORD dst_unused:UNUSED_PAD src0_sel:WORD_1 src1_sel:DWORD
	v_and_b32_sdwa v28, v23, v152 dst_sel:DWORD dst_unused:UNUSED_PAD src0_sel:WORD_1 src1_sel:DWORD
	v_add3_u32 v25, v25, v27, s87
	v_add3_u32 v23, v23, v28, s87
	v_and_b32_e32 v25, 0xffff0000, v25
	v_and_b32_e32 v27, 0xffff0000, v23
	v_or_b32_sdwa v23, v25, v24 dst_sel:DWORD dst_unused:UNUSED_PAD src0_sel:DWORD src1_sel:WORD_1
	v_or_b32_sdwa v22, v27, v22 dst_sel:DWORD dst_unused:UNUSED_PAD src0_sel:DWORD src1_sel:WORD_1
	global_store_dwordx2 v[12:13], v[22:23], off offset:512
	global_load_dwordx4 v[22:25], v[14:15], off offset:2048 nt
	s_waitcnt vmcnt(0)
	v_mul_f32_e32 v27, v23, v23
	v_fmac_f32_e32 v27, v22, v22
	v_fmac_f32_e32 v27, v24, v24
	v_fmac_f32_e32 v27, v25, v25
	v_add_f32_e32 v26, v26, v27
	v_and_b32_sdwa v27, v24, v152 dst_sel:DWORD dst_unused:UNUSED_PAD src0_sel:WORD_1 src1_sel:DWORD
	v_and_b32_sdwa v28, v22, v152 dst_sel:DWORD dst_unused:UNUSED_PAD src0_sel:WORD_1 src1_sel:DWORD
	v_add3_u32 v22, v22, v28, s87
	v_add3_u32 v24, v24, v27, s87
	v_and_b32_sdwa v27, v25, v152 dst_sel:DWORD dst_unused:UNUSED_PAD src0_sel:WORD_1 src1_sel:DWORD
	v_and_b32_sdwa v28, v23, v152 dst_sel:DWORD dst_unused:UNUSED_PAD src0_sel:WORD_1 src1_sel:DWORD
	v_add3_u32 v25, v25, v27, s87
	v_add3_u32 v23, v23, v28, s87
	v_and_b32_e32 v25, 0xffff0000, v25
	v_and_b32_e32 v27, 0xffff0000, v23
	v_or_b32_sdwa v23, v25, v24 dst_sel:DWORD dst_unused:UNUSED_PAD src0_sel:DWORD src1_sel:WORD_1
	v_or_b32_sdwa v22, v27, v22 dst_sel:DWORD dst_unused:UNUSED_PAD src0_sel:DWORD src1_sel:WORD_1
	global_store_dwordx2 v[12:13], v[22:23], off offset:1024
	global_load_dwordx4 v[22:25], v[14:15], off offset:3072 nt
	s_waitcnt vmcnt(0)
	v_mul_f32_e32 v14, v23, v23
	v_fmac_f32_e32 v14, v22, v22
	v_fmac_f32_e32 v14, v24, v24
	v_fmac_f32_e32 v14, v25, v25
	v_add_f32_e32 v26, v26, v14
	v_and_b32_sdwa v14, v24, v152 dst_sel:DWORD dst_unused:UNUSED_PAD src0_sel:WORD_1 src1_sel:DWORD
	v_and_b32_sdwa v15, v22, v152 dst_sel:DWORD dst_unused:UNUSED_PAD src0_sel:WORD_1 src1_sel:DWORD
	v_add3_u32 v22, v22, v15, s87
	v_add3_u32 v14, v24, v14, s87
	v_and_b32_sdwa v15, v25, v152 dst_sel:DWORD dst_unused:UNUSED_PAD src0_sel:WORD_1 src1_sel:DWORD
	v_and_b32_sdwa v24, v23, v152 dst_sel:DWORD dst_unused:UNUSED_PAD src0_sel:WORD_1 src1_sel:DWORD
	v_add3_u32 v15, v25, v15, s87
	v_add3_u32 v23, v23, v24, s87
	v_and_b32_e32 v15, 0xffff0000, v15
	v_and_b32_e32 v23, 0xffff0000, v23
	v_or_b32_sdwa v15, v15, v14 dst_sel:DWORD dst_unused:UNUSED_PAD src0_sel:DWORD src1_sel:WORD_1
	v_or_b32_sdwa v14, v23, v22 dst_sel:DWORD dst_unused:UNUSED_PAD src0_sel:DWORD src1_sel:WORD_1
	global_store_dwordx2 v[12:13], v[14:15], off offset:1536
	ds_bpermute_b32 v12, v16, v26
	s_waitcnt lgkmcnt(0)
	v_add_f32_e32 v12, v26, v12
	ds_bpermute_b32 v13, v17, v12
	s_waitcnt lgkmcnt(0)
	v_add_f32_e32 v12, v12, v13
	ds_bpermute_b32 v13, v18, v12
	s_waitcnt lgkmcnt(0)
	v_add_f32_e32 v12, v12, v13
	ds_bpermute_b32 v13, v19, v12
	s_waitcnt lgkmcnt(0)
	v_add_f32_e32 v12, v12, v13
	ds_bpermute_b32 v13, v20, v12
	s_waitcnt lgkmcnt(0)
	v_add_f32_e32 v12, v12, v13
	ds_bpermute_b32 v13, v21, v12
	s_and_saveexec_b64 s[0:1], vcc
	s_cbranch_execz .LBB0_547
	s_waitcnt lgkmcnt(0)
	v_add_f32_e32 v12, v12, v13
	v_cndmask_b32_e64 v12, 0, v12, s[4:5]
	v_lshl_add_u64 v[10:11], v[10:11], 4, v[6:7]
	global_store_dword v[10:11], v12, off
	s_branch .LBB0_547
